# static priority also in the RG-LRU scan units (waves 4-7 at s_setprio 1, reset at every step start); otherwise as v73
# baseline (speedup 1.0000x reference)
.LBB0_10:
	s_setprio 0
	s_cmp_eq_u32 s21, 0
	s_mov_b32 s20, s35
	s_mov_b32 s0, s35
	s_mov_b32 s8, s35
	s_cbranch_scc1 .LBB0_49
	s_cmp_gt_i32 s21, 16
	s_mov_b64 s[4:5], -1
	s_cbranch_scc0 .LBB0_27
	s_cmp_eq_u32 s21, 17
	s_cbranch_scc1 .LBB0_31
	s_sub_i32 s0, s21, 18
	s_mul_hi_u32 s1, s0, 0x24924925
	s_sub_i32 s3, s0, s1
	s_lshr_b32 s3, s3, 1
	s_add_i32 s3, s3, s1
	s_lshr_b32 s3, s3, 2
	s_mul_i32 s1, s3, 7
	s_sub_i32 s11, s0, s1
	s_cmp_gt_u32 s11, 4
	s_cselect_b64 s[0:1], -1, 0
	v_cndmask_b32_e64 v0, 0, 1, s[0:1]
	s_mov_b64 s[8:9], -1
	v_readfirstlane_b32 s10, v0
	s_mov_b64 s[4:5], 0
	s_cmp_lt_i32 s11, 2
	s_mov_b64 s[0:1], 0
	s_waitcnt lgkmcnt(0)
	s_mov_b64 s[6:7], 0
	s_cbranch_scc1 .LBB0_32
	s_cmp_gt_i32 s11, 4
	s_cbranch_scc0 .LBB0_17
	s_mov_b64 s[8:9], 0
	s_cmp_gt_i32 s11, 5
	s_cbranch_scc0 .LBB0_17
	s_cmp_eq_u32 s11, 6
	s_mov_b64 s[0:1], -1
	s_cselect_b64 s[6:7], -1, 0

.LBB0_401:
	s_cmpk_lt_u32 s81, 0x100
	s_cbranch_scc1 .Lsc_np401
	s_setprio 1
